# NA: batch tile-A bias LDS reads (16 reads, counted waits) and drop redundant lgkmcnt(0) between same-wave K LDS write and fragment read
# baseline (speedup 1.0000x reference)
.LBB0_611:
	s_waitcnt vmcnt(12)
	ds_write_b128 v184, v[64:67] offset:46080
	ds_write_b128 v184, v[68:71] offset:47232
	ds_write_b128 v184, v[72:75] offset:48384
	ds_write_b128 v184, v[76:79] offset:49536
	ds_read_b128 v[64:67], v185 offset:46080
	ds_read_b128 v[68:71], v185 offset:46112
	ds_read_b128 v[72:75], v185 offset:46144
	ds_read_b128 v[76:79], v185 offset:46176
	s_add_i32 s81, s93, 14
	s_add_i32 s33, s93, 16
	s_cmp_ge_u32 s33, s84
	s_waitcnt vmcnt(11)
	ds_write_b128 v184, v[80:83]
	s_waitcnt vmcnt(8)
	ds_write_b128 v184, v[92:95] offset:1152
	ds_write_b128 v184, v[88:91] offset:2304
	ds_write_b128 v184, v[84:87] offset:3456
	s_waitcnt lgkmcnt(4)
	v_mfma_f32_32x32x16_bf16 v[32:47], v[64:67], v[48:51], 0
	v_mfma_f32_32x32x16_bf16 v[32:47], v[68:71], v[52:55], v[32:47]
	v_mfma_f32_32x32x16_bf16 v[32:47], v[72:75], v[56:59], v[32:47]
	v_mfma_f32_32x32x16_bf16 v[32:47], v[76:79], v[60:63], v[32:47]
	s_cbranch_scc1 .LBB0_617
	s_cmp_lt_u32 s81, 14
	s_cselect_b64 s[0:1], -1, 0
	s_and_b64 s[0:1], s[76:77], s[0:1]
	s_andn2_b64 vcc, exec, s[0:1]
	s_mov_b64 s[0:1], -1
	s_cbranch_vccz .LBB0_614
	s_and_b64 s[0:1], s[76:77], exec
	s_cselect_b32 s0, s93, s33
	s_lshl_b32 s0, s0, 5
	s_add_i32 s68, s0, s86
	s_mov_b64 s[0:1], 0

.LBB0_617:
	s_cmp_lt_u32 s81, 16
	s_cselect_b64 s[0:1], -1, 0
	s_and_b64 s[0:1], s[76:77], s[0:1]
	v_cndmask_b32_e64 v222, 0, 1, s[0:1]
	v_cmp_ne_u32_e64 s[68:69], 1, v222
	s_andn2_b64 vcc, exec, s[0:1]
	s_cbranch_vccnz .LBB0_619
	v_add_u32_e32 v222, s83, v231
	v_add_u32_e32 v223, s83, v221
	v_add_u32_e32 v224, s83, v220
	v_add_u32_e32 v225, s83, v219
	v_add_u32_e32 v148, s83, v218
	v_add_u32_e32 v149, s83, v217
	v_add_u32_e32 v150, s83, v216
	v_add_u32_e32 v151, s83, v215
	v_add_u32_e32 v152, s83, v214
	v_add_u32_e32 v153, s83, v213
	v_add_u32_e32 v154, s83, v212
	v_add_u32_e32 v155, s83, v211
	s_waitcnt lgkmcnt(3)
	ds_read_b32 v222, v222 offset:4668
	ds_read_b32 v223, v223 offset:4672
	ds_read_b32 v224, v224 offset:4676
	ds_read_b32 v225, v225 offset:4680
	ds_read_b32 v148, v148 offset:4700
	ds_read_b32 v149, v149 offset:4704
	ds_read_b32 v150, v150 offset:4708
	ds_read_b32 v151, v151 offset:4712
	ds_read_b32 v152, v152 offset:4608
	ds_read_b32 v153, v153 offset:4608
	ds_read_b32 v154, v154 offset:4608
	ds_read_b32 v155, v155 offset:4608
	v_add_u32_e32 v156, s83, v210
	v_add_u32_e32 v157, s83, v209
	v_add_u32_e32 v158, s83, v208
	v_add_u32_e32 v159, s83, v207
	s_waitcnt lgkmcnt(8)
	ds_read_b32 v156, v156 offset:4608
	ds_read_b32 v157, v157 offset:4608
	ds_read_b32 v158, v158 offset:4608
	ds_read_b32 v159, v159 offset:4608
	v_pk_add_f32 v[32:33], v[32:33], v[222:223]
	v_pk_add_f32 v[34:35], v[34:35], v[224:225]
	s_waitcnt lgkmcnt(8)
	v_pk_add_f32 v[36:37], v[36:37], v[148:149]
	v_pk_add_f32 v[38:39], v[38:39], v[150:151]
	s_waitcnt lgkmcnt(4)
	v_pk_add_f32 v[40:41], v[40:41], v[152:153]
	v_pk_add_f32 v[42:43], v[42:43], v[154:155]
	s_waitcnt lgkmcnt(0)
	v_pk_add_f32 v[44:45], v[44:45], v[156:157]
	v_pk_add_f32 v[46:47], v[46:47], v[158:159]
	v_cndmask_b32_e64 v32, v32, v230, s[2:3]
	v_cndmask_b32_e64 v33, v33, v230, s[6:7]
	v_cndmask_b32_e64 v34, v34, v230, s[4:5]
	v_cndmask_b32_e64 v35, v35, v230, s[10:11]
	v_cndmask_b32_e64 v36, v36, v230, s[8:9]
	v_cndmask_b32_e64 v37, v37, v230, s[14:15]
	v_cndmask_b32_e64 v38, v38, v230, s[12:13]
	v_cndmask_b32_e64 v39, v39, v230, s[16:17]
	v_cndmask_b32_e64 v40, v230, v40, s[18:19]
	v_cndmask_b32_e64 v41, v230, v41, s[20:21]
	v_cndmask_b32_e64 v42, v230, v42, s[22:23]
	v_cndmask_b32_e64 v43, v230, v43, s[24:25]
	v_cndmask_b32_e64 v44, v230, v44, s[26:27]
	v_cndmask_b32_e64 v45, v230, v45, s[28:29]
	v_cndmask_b32_e64 v46, v230, v46, s[30:31]
	v_cndmask_b32_e64 v47, v230, v47, s[34:35]
.LBB0_619:
	s_nop 3
	v_max_f32_e32 v222, v33, v33
	v_max_f32_e32 v223, v32, v32
	v_max_f32_e32 v222, v223, v222
	v_max3_f32 v222, v222, v34, v35
	v_max3_f32 v222, v222, v36, v37
	v_max3_f32 v222, v222, v38, v39
	v_max3_f32 v222, v222, v40, v41
	v_max3_f32 v222, v222, v42, v43
	v_max3_f32 v222, v222, v44, v45
	v_max3_f32 v222, v222, v46, v47
	ds_bpermute_b32 v223, v169, v222
	s_waitcnt lgkmcnt(0)
	s_add_i32 s0, s93, 17
	s_cmp_ge_u32 s0, s84
	s_waitcnt lgkmcnt(0)
	v_max3_f32 v233, v140, v222, v223
	v_sub_f32_e32 v32, v32, v233
	v_exp_f32_e32 v234, v32
	v_sub_f32_e32 v32, v33, v233
	v_exp_f32_e32 v235, v32
	v_sub_f32_e32 v32, v34, v233
	v_exp_f32_e32 v236, v32
	v_sub_f32_e32 v32, v35, v233
	v_exp_f32_e32 v237, v32
	v_sub_f32_e32 v32, v36, v233
	v_exp_f32_e32 v238, v32
	v_sub_f32_e32 v32, v37, v233
	v_exp_f32_e32 v239, v32
	v_sub_f32_e32 v32, v38, v233
	v_exp_f32_e32 v240, v32
	v_sub_f32_e32 v32, v39, v233
	v_exp_f32_e32 v241, v32
	v_sub_f32_e32 v32, v40, v233
	v_exp_f32_e32 v242, v32
	v_sub_f32_e32 v32, v41, v233
	v_exp_f32_e32 v243, v32
	v_sub_f32_e32 v32, v42, v233
	v_exp_f32_e32 v244, v32
	v_sub_f32_e32 v32, v43, v233
	ds_read_b64_tr_b16 v[36:37], v229
	ds_read_b64_tr_b16 v[38:39], v229 offset:1152
	ds_read_b64_tr_b16 v[148:149], v229 offset:64
	ds_read_b64_tr_b16 v[150:151], v229 offset:1216
	ds_read_b64_tr_b16 v[152:153], v229 offset:2304
	ds_read_b64_tr_b16 v[154:155], v229 offset:3456
	ds_read_b64_tr_b16 v[156:157], v229 offset:2368
	ds_read_b64_tr_b16 v[158:159], v229 offset:3520
	v_sub_f32_e32 v140, v140, v233
	v_exp_f32_e32 v245, v32
	v_sub_f32_e32 v32, v44, v233
	v_exp_f32_e32 v140, v140
	v_exp_f32_e32 v246, v32
	v_sub_f32_e32 v32, v45, v233
	v_exp_f32_e32 v247, v32
	v_sub_f32_e32 v32, v46, v233
	v_exp_f32_e32 v248, v32
	v_sub_f32_e32 v32, v47, v233
	v_exp_f32_e32 v249, v32
	v_cvt_pk_bf16_f32 v32, v234, v235
	v_cvt_pk_bf16_f32 v33, v236, v237
	v_cvt_pk_bf16_f32 v34, v238, v239
	v_cvt_pk_bf16_f32 v35, v240, v241
	v_pk_mul_f32 v[30:31], v[30:31], v[140:141] op_sel_hi:[1,0]
	v_pk_mul_f32 v[28:29], v[28:29], v[140:141] op_sel_hi:[1,0]
	v_pk_mul_f32 v[26:27], v[26:27], v[140:141] op_sel_hi:[1,0]
	v_pk_mul_f32 v[24:25], v[24:25], v[140:141] op_sel_hi:[1,0]
	v_pk_mul_f32 v[22:23], v[22:23], v[140:141] op_sel_hi:[1,0]
	v_pk_mul_f32 v[20:21], v[20:21], v[140:141] op_sel_hi:[1,0]
	v_pk_mul_f32 v[18:19], v[18:19], v[140:141] op_sel_hi:[1,0]
	v_pk_mul_f32 v[16:17], v[16:17], v[140:141] op_sel_hi:[1,0]
	v_pk_mul_f32 v[14:15], v[14:15], v[140:141] op_sel_hi:[1,0]
	v_pk_mul_f32 v[12:13], v[12:13], v[140:141] op_sel_hi:[1,0]
	s_waitcnt lgkmcnt(6)
	v_mfma_f32_32x32x16_bf16 v[16:31], v[36:39], v[32:35], v[16:31]
	v_pk_mul_f32 v[10:11], v[10:11], v[140:141] op_sel_hi:[1,0]
	v_pk_mul_f32 v[8:9], v[8:9], v[140:141] op_sel_hi:[1,0]
	v_pk_mul_f32 v[6:7], v[6:7], v[140:141] op_sel_hi:[1,0]
	v_pk_mul_f32 v[4:5], v[4:5], v[140:141] op_sel_hi:[1,0]
	v_pk_mul_f32 v[2:3], v[2:3], v[140:141] op_sel_hi:[1,0]
	v_pk_mul_f32 v[0:1], v[0:1], v[140:141] op_sel_hi:[1,0]
	s_nop 1
	s_waitcnt lgkmcnt(4)
	v_mfma_f32_32x32x16_bf16 v[0:15], v[148:151], v[32:35], v[0:15]
	v_cvt_pk_bf16_f32 v32, v242, v243
	v_cvt_pk_bf16_f32 v33, v244, v245
	v_cvt_pk_bf16_f32 v34, v246, v247
	v_cvt_pk_bf16_f32 v35, v248, v249
	s_nop 1
	s_waitcnt lgkmcnt(2)
	v_mfma_f32_32x32x16_bf16 v[16:31], v[152:155], v[32:35], v[16:31]
	s_waitcnt lgkmcnt(2)
	s_waitcnt lgkmcnt(0)
	s_waitcnt vmcnt(3)
	ds_write_b128 v184, v[96:99] offset:46080
	ds_write_b128 v184, v[100:103] offset:47232
	ds_write_b128 v184, v[104:107] offset:48384
	ds_write_b128 v184, v[108:111] offset:49536
	ds_read_b128 v[96:99], v185 offset:46080
	ds_read_b128 v[100:103], v185 offset:46112
	ds_read_b128 v[104:107], v185 offset:46144
	ds_read_b128 v[108:111], v185 offset:46176
	ds_write_b128 v184, v[112:115]
	s_waitcnt vmcnt(0)
	ds_write_b128 v184, v[124:127] offset:1152
	ds_write_b128 v184, v[120:123] offset:2304
	ds_write_b128 v184, v[116:119] offset:3456
	v_mfma_f32_32x32x16_bf16 v[0:15], v[156:159], v[32:35], v[0:15]
	s_waitcnt lgkmcnt(4)
	v_mfma_f32_32x32x16_bf16 v[32:47], v[96:99], v[48:51], 0
	v_mfma_f32_32x32x16_bf16 v[32:47], v[100:103], v[52:55], v[32:47]
	v_mfma_f32_32x32x16_bf16 v[32:47], v[104:107], v[56:59], v[32:47]
	v_mfma_f32_32x32x16_bf16 v[32:47], v[108:111], v[60:63], v[32:47]
	s_cbranch_scc1 .LBB0_623
	s_cmp_lt_u32 s81, 13
	s_cselect_b64 vcc, -1, 0
	s_and_b64 vcc, s[76:77], vcc
	s_and_b64 vcc, exec, vcc
	s_mov_b32 s1, s87
	s_cbranch_vccnz .LBB0_622
	s_add_i32 s1, s93, 1
	s_and_b64 vcc, s[76:77], exec
	s_cselect_b32 s0, s1, s0
	s_lshl_b32 s0, s0, 5
	s_add_i32 s1, s0, s86
